# residual epilogues (w_out, ff2) software-pipelined: batch q+1 loads issued before batch q stores into already-consumed accumulator registers, vmcnt(8) waits
# speedup vs baseline: 1.0132x; 1.0011x over previous
; #define ERES_LOAD(q, bj, n) do { _Pragma("unroll") for (int ai = 0; ai < 2; ++ai) _Pragma("unroll") for (int m = 0; m < 4; ++m) \
;             tb[q][ai * 4 + m] = *(const GAS f32x4*)(bp + (size_t)(ai * HALF + m * 16) * DM + (bj) * HALF + (n) * 16); } while (0)
; #define ERES_STORE(q, bj, n) do { const f32x4 gv = *(const GAS f32x4*)(gp + (bj) * HALF + (n) * 16); \
;             _Pragma("unroll") for (int ai = 0; ai < 2; ++ai) _Pragma("unroll") for (int m = 0; m < 4; ++m) \
;                 *(GAS f32x4*)(op + (size_t)(ai * HALF + m * 16) * DM + (bj) * HALF + (n) * 16) = tb[q][ai * 4 + m] + gv * acc[ai][bj][m][n]; } while (0)
;     __device__ __forceinline__ void operator()(const f32x4 (&acc)[2][2][4][2], const Unit& u, int wr, int wc, int fr, int fq) const {
;     ...
;         const float* bp = (u.pm < 32 ? base_lat + (size_t)row0 * DM : base_ctx + (size_t)(row0 - NLAT) * DM) + col0;
;         float* op = out + (size_t)row0 * DM + col0;
;         f32x4 tb[1][8];
;     ...
; #pragma unroll
;         for (int bj = 0; bj < 2; ++bj)
; #pragma unroll
;             for (int n = 0; n < 2; ++n) { ERES_LOAD(0, bj, n); asm volatile("" ::: "memory"); ERES_STORE(0, bj, n); asm volatile("" ::: "memory"); }
.LBB0_125:
	v_lshlrev_b64 v[150:151], 2, v[138:139]
	v_lshl_add_u64 v[146:147], v[144:145], 0, v[150:151]
	v_add_co_u32_e32 v148, vcc, 0x20000, v146
	s_mov_b32 s17, 0x120000
	s_nop 0
	v_addc_co_u32_e32 v149, vcc, 0, v147, vcc
	v_add_co_u32_e32 v152, vcc, 0x40000, v146
	global_load_dwordx4 v[178:181], v[146:147], off
	global_load_dwordx4 v[182:185], v[148:149], off
	v_addc_co_u32_e32 v153, vcc, 0, v147, vcc
	v_add_co_u32_e32 v154, vcc, 0x60000, v146
	v_lshl_add_u64 v[142:143], s[10:11], 0, v[142:143]
	s_nop 0
	v_addc_co_u32_e32 v155, vcc, 0, v147, vcc
	v_add_co_u32_e32 v158, vcc, 0x100000, v146
	global_load_dwordx4 v[186:189], v[152:153], off
	global_load_dwordx4 v[190:193], v[154:155], off
	v_addc_co_u32_e32 v159, vcc, 0, v147, vcc
	v_add_co_u32_e32 v160, vcc, s17, v146
	v_lshl_add_u64 v[142:143], v[142:143], 0, v[150:151]
	s_nop 0
	v_addc_co_u32_e32 v161, vcc, 0, v147, vcc
	v_add_co_u32_e32 v162, vcc, 0x140000, v146
	global_load_dwordx4 v[210:213], v[158:159], off
	global_load_dwordx4 v[214:217], v[160:161], off
	v_addc_co_u32_e32 v163, vcc, 0, v147, vcc
	v_add_co_u32_e32 v166, vcc, 0x160000, v146
	s_mov_b32 s19, 0x20000
	s_nop 0
	v_addc_co_u32_e32 v167, vcc, 0, v147, vcc
	global_load_dwordx4 v[218:221], v[162:163], off
	global_load_dwordx4 v[222:225], v[166:167], off
	global_load_dwordx4 v[240:243], v[136:137], off
	v_add_co_u32_e32 v144, vcc, s19, v142
	s_mov_b32 s19, 0x40000
	s_nop 0
	v_addc_co_u32_e32 v145, vcc, 0, v143, vcc
	v_add_co_u32_e32 v150, vcc, s19, v142
	s_mov_b32 s19, 0x60000
	s_nop 0
	v_addc_co_u32_e32 v151, vcc, 0, v143, vcc
	v_add_co_u32_e32 v156, vcc, s19, v142
	s_mov_b32 s19, 0x100000
	s_nop 0
	v_addc_co_u32_e32 v157, vcc, 0, v143, vcc
	v_add_co_u32_e32 v164, vcc, s19, v142
	s_nop 1
	v_addc_co_u32_e32 v165, vcc, 0, v143, vcc
	v_add_co_u32_e32 v168, vcc, s17, v142
	s_mov_b32 s17, 0x140000
	s_nop 0
	v_addc_co_u32_e32 v169, vcc, 0, v143, vcc
	v_add_co_u32_e32 v170, vcc, s17, v142
	s_mov_b32 s17, 0x160000
	s_nop 0
	v_addc_co_u32_e32 v171, vcc, 0, v143, vcc
	v_add_co_u32_e32 v172, vcc, s17, v142
	s_waitcnt vmcnt(0)
	v_pk_fma_f32 v[180:181], v[128:129], v[242:243], v[180:181]
	v_pk_fma_f32 v[178:179], v[126:127], v[240:241], v[178:179]
	v_pk_fma_f32 v[184:185], v[124:125], v[242:243], v[184:185]
	v_pk_fma_f32 v[182:183], v[122:123], v[240:241], v[182:183]
	v_pk_fma_f32 v[188:189], v[120:121], v[242:243], v[188:189]
	v_pk_fma_f32 v[186:187], v[118:119], v[240:241], v[186:187]
	v_pk_fma_f32 v[192:193], v[116:117], v[242:243], v[192:193]
	v_pk_fma_f32 v[190:191], v[114:115], v[240:241], v[190:191]
	v_pk_fma_f32 v[212:213], v[112:113], v[242:243], v[212:213]
	v_pk_fma_f32 v[210:211], v[110:111], v[240:241], v[210:211]
	v_pk_fma_f32 v[216:217], v[108:109], v[242:243], v[216:217]
	v_pk_fma_f32 v[214:215], v[106:107], v[240:241], v[214:215]
	v_pk_fma_f32 v[220:221], v[104:105], v[242:243], v[220:221]
	v_pk_fma_f32 v[218:219], v[102:103], v[240:241], v[218:219]
	global_load_dwordx4 v[126:129], v[146:147], off offset:64
	global_load_dwordx4 v[122:125], v[148:149], off offset:64
	global_load_dwordx4 v[118:121], v[152:153], off offset:64
	global_load_dwordx4 v[114:117], v[154:155], off offset:64
	global_load_dwordx4 v[110:113], v[158:159], off offset:64
	global_load_dwordx4 v[106:109], v[160:161], off offset:64
	global_load_dwordx4 v[102:105], v[162:163], off offset:64
	global_load_dwordx4 v[202:205], v[166:167], off offset:64
	global_load_dwordx4 v[244:247], v[136:137], off offset:64
	global_store_dwordx4 v[142:143], v[178:181], off
	global_store_dwordx4 v[144:145], v[182:185], off
	global_store_dwordx4 v[150:151], v[186:189], off
	global_store_dwordx4 v[156:157], v[190:193], off
	global_store_dwordx4 v[164:165], v[210:213], off
	global_store_dwordx4 v[168:169], v[214:217], off
	global_store_dwordx4 v[170:171], v[218:221], off
	v_pk_fma_f32 v[180:181], v[100:101], v[242:243], v[224:225]
	v_pk_fma_f32 v[178:179], v[98:99], v[240:241], v[222:223]
	v_addc_co_u32_e32 v173, vcc, 0, v143, vcc
	global_store_dwordx4 v[172:173], v[178:181], off
	s_waitcnt vmcnt(8)
; #define ERES_LOAD(q, bj, n) do { _Pragma("unroll") for (int ai = 0; ai < 2; ++ai) _Pragma("unroll") for (int m = 0; m < 4; ++m) \
;             tb[q][ai * 4 + m] = *(const GAS f32x4*)(bp + (size_t)(ai * HALF + m * 16) * DM + (bj) * HALF + (n) * 16); } while (0)
; #define ERES_STORE(q, bj, n) do { const f32x4 gv = *(const GAS f32x4*)(gp + (bj) * HALF + (n) * 16); \
;             _Pragma("unroll") for (int ai = 0; ai < 2; ++ai) _Pragma("unroll") for (int m = 0; m < 4; ++m) \
;                 *(GAS f32x4*)(op + (size_t)(ai * HALF + m * 16) * DM + (bj) * HALF + (n) * 16) = tb[q][ai * 4 + m] + gv * acc[ai][bj][m][n]; } while (0)
;     __device__ __forceinline__ void operator()(const f32x4 (&acc)[2][2][4][2], const Unit& u, int wr, int wc, int fr, int fq) const {
;     ...
; #pragma unroll
;         for (int bj = 0; bj < 2; ++bj)
; #pragma unroll
;             for (int n = 0; n < 2; ++n) { ERES_LOAD(0, bj, n); asm volatile("" ::: "memory"); ERES_STORE(0, bj, n); asm volatile("" ::: "memory"); }
	v_pk_fma_f32 v[128:129], v[96:97], v[246:247], v[128:129]
	v_pk_fma_f32 v[126:127], v[94:95], v[244:245], v[126:127]
	v_pk_fma_f32 v[124:125], v[92:93], v[246:247], v[124:125]
	v_pk_fma_f32 v[122:123], v[90:91], v[244:245], v[122:123]
	v_pk_fma_f32 v[120:121], v[88:89], v[246:247], v[120:121]
	v_pk_fma_f32 v[118:119], v[86:87], v[244:245], v[118:119]
	v_pk_fma_f32 v[116:117], v[84:85], v[246:247], v[116:117]
	v_pk_fma_f32 v[114:115], v[82:83], v[244:245], v[114:115]
	v_pk_fma_f32 v[112:113], v[80:81], v[246:247], v[112:113]
	v_pk_fma_f32 v[110:111], v[78:79], v[244:245], v[110:111]
	v_pk_fma_f32 v[108:109], v[76:77], v[246:247], v[108:109]
	v_pk_fma_f32 v[106:107], v[74:75], v[244:245], v[106:107]
	v_pk_fma_f32 v[104:105], v[72:73], v[246:247], v[104:105]
	v_pk_fma_f32 v[102:103], v[70:71], v[244:245], v[102:103]
	v_pk_fma_f32 v[204:205], v[68:69], v[246:247], v[204:205]
	v_pk_fma_f32 v[202:203], v[66:67], v[244:245], v[202:203]
	global_load_dwordx4 v[178:181], v[146:147], off offset:512
	global_load_dwordx4 v[182:185], v[148:149], off offset:512
	global_load_dwordx4 v[186:189], v[152:153], off offset:512
	global_load_dwordx4 v[190:193], v[154:155], off offset:512
	global_load_dwordx4 v[210:213], v[158:159], off offset:512
	global_load_dwordx4 v[214:217], v[160:161], off offset:512
	global_load_dwordx4 v[218:221], v[162:163], off offset:512
	global_load_dwordx4 v[222:225], v[166:167], off offset:512
	global_load_dwordx4 v[240:243], v[136:137], off offset:512
	global_store_dwordx4 v[142:143], v[126:129], off offset:64
	global_store_dwordx4 v[144:145], v[122:125], off offset:64
	global_store_dwordx4 v[150:151], v[118:121], off offset:64
	global_store_dwordx4 v[156:157], v[114:117], off offset:64
	global_store_dwordx4 v[164:165], v[110:113], off offset:64
	global_store_dwordx4 v[168:169], v[106:109], off offset:64
	global_store_dwordx4 v[170:171], v[102:105], off offset:64
	global_store_dwordx4 v[172:173], v[202:205], off offset:64
	s_waitcnt vmcnt(8)
	v_pk_fma_f32 v[180:181], v[64:65], v[242:243], v[180:181]
	v_pk_fma_f32 v[178:179], v[62:63], v[240:241], v[178:179]
	v_pk_fma_f32 v[184:185], v[60:61], v[242:243], v[184:185]
	v_pk_fma_f32 v[182:183], v[58:59], v[240:241], v[182:183]
	v_pk_fma_f32 v[188:189], v[56:57], v[242:243], v[188:189]
	v_pk_fma_f32 v[186:187], v[54:55], v[240:241], v[186:187]
	v_pk_fma_f32 v[192:193], v[52:53], v[242:243], v[192:193]
	v_pk_fma_f32 v[190:191], v[50:51], v[240:241], v[190:191]
	v_pk_fma_f32 v[212:213], v[48:49], v[242:243], v[212:213]
	v_pk_fma_f32 v[210:211], v[46:47], v[240:241], v[210:211]
	v_pk_fma_f32 v[216:217], v[44:45], v[242:243], v[216:217]
	v_pk_fma_f32 v[214:215], v[42:43], v[240:241], v[214:215]
	v_pk_fma_f32 v[220:221], v[36:37], v[242:243], v[220:221]
	v_pk_fma_f32 v[218:219], v[34:35], v[240:241], v[218:219]
	v_pk_fma_f32 v[224:225], v[28:29], v[242:243], v[224:225]
	v_pk_fma_f32 v[222:223], v[26:27], v[240:241], v[222:223]
	global_load_dwordx4 v[126:129], v[146:147], off offset:576
	s_nop 0
	global_load_dwordx4 v[122:125], v[148:149], off offset:576
	s_nop 0
	global_load_dwordx4 v[118:121], v[152:153], off offset:576
	s_nop 0
	global_load_dwordx4 v[114:117], v[154:155], off offset:576
	s_nop 0
	global_load_dwordx4 v[110:113], v[158:159], off offset:576
	s_nop 0
	global_load_dwordx4 v[106:109], v[160:161], off offset:576
	s_nop 0
	global_load_dwordx4 v[102:105], v[162:163], off offset:576
	global_load_dwordx4 v[202:205], v[166:167], off offset:576
	global_load_dwordx4 v[244:247], v[136:137], off offset:576
	global_store_dwordx4 v[142:143], v[178:181], off offset:512
	global_store_dwordx4 v[144:145], v[182:185], off offset:512
	global_store_dwordx4 v[150:151], v[186:189], off offset:512
	global_store_dwordx4 v[156:157], v[190:193], off offset:512
	global_store_dwordx4 v[164:165], v[210:213], off offset:512
	global_store_dwordx4 v[168:169], v[214:217], off offset:512
	global_store_dwordx4 v[170:171], v[218:221], off offset:512
	global_store_dwordx4 v[172:173], v[222:225], off offset:512
	s_waitcnt vmcnt(8)
	v_pk_fma_f32 v[128:129], v[40:41], v[246:247], v[128:129]
	v_pk_fma_f32 v[126:127], v[38:39], v[244:245], v[126:127]
	v_pk_fma_f32 v[124:125], v[32:33], v[246:247], v[124:125]
	v_pk_fma_f32 v[122:123], v[30:31], v[244:245], v[122:123]
	v_pk_fma_f32 v[120:121], v[24:25], v[246:247], v[120:121]
	v_pk_fma_f32 v[118:119], v[22:23], v[244:245], v[118:119]
	v_pk_fma_f32 v[116:117], v[20:21], v[246:247], v[116:117]
	v_pk_fma_f32 v[114:115], v[18:19], v[244:245], v[114:115]
	v_pk_fma_f32 v[112:113], v[16:17], v[246:247], v[112:113]
	v_pk_fma_f32 v[110:111], v[14:15], v[244:245], v[110:111]
	v_pk_fma_f32 v[108:109], v[12:13], v[246:247], v[108:109]
	v_pk_fma_f32 v[106:107], v[10:11], v[244:245], v[106:107]
	v_pk_fma_f32 v[104:105], v[8:9], v[246:247], v[104:105]
	v_pk_fma_f32 v[102:103], v[6:7], v[244:245], v[102:103]
	v_pk_fma_f32 v[204:205], v[4:5], v[246:247], v[204:205]
	v_pk_fma_f32 v[202:203], v[2:3], v[244:245], v[202:203]
	global_store_dwordx4 v[142:143], v[126:129], off offset:576
	global_store_dwordx4 v[144:145], v[122:125], off offset:576
	global_store_dwordx4 v[150:151], v[118:121], off offset:576
	global_store_dwordx4 v[156:157], v[114:117], off offset:576
	global_store_dwordx4 v[164:165], v[110:113], off offset:576
	global_store_dwordx4 v[168:169], v[106:109], off offset:576
	global_store_dwordx4 v[170:171], v[102:105], off offset:576
	global_store_dwordx4 v[172:173], v[202:205], off offset:576

; #define ERES_LOAD(q, bj, n) do { _Pragma("unroll") for (int ai = 0; ai < 2; ++ai) _Pragma("unroll") for (int m = 0; m < 4; ++m) \
;             tb[q][ai * 4 + m] = *(const GAS f32x4*)(bp + (size_t)(ai * HALF + m * 16) * DM + (bj) * HALF + (n) * 16); } while (0)
; #define ERES_STORE(q, bj, n) do { const f32x4 gv = *(const GAS f32x4*)(gp + (bj) * HALF + (n) * 16); \
;             _Pragma("unroll") for (int ai = 0; ai < 2; ++ai) _Pragma("unroll") for (int m = 0; m < 4; ++m) \
;                 *(GAS f32x4*)(op + (size_t)(ai * HALF + m * 16) * DM + (bj) * HALF + (n) * 16) = tb[q][ai * 4 + m] + gv * acc[ai][bj][m][n]; } while (0)
;     __device__ __forceinline__ void operator()(const f32x4 (&acc)[2][2][4][2], const Unit& u, int wr, int wc, int fr, int fq) const {
;     ...
;         const float* bp = (u.pm < 32 ? base_lat + (size_t)row0 * DM : base_ctx + (size_t)(row0 - NLAT) * DM) + col0;
;         float* op = out + (size_t)row0 * DM + col0;
;         f32x4 tb[1][8];
;     ...
; #pragma unroll
;         for (int bj = 0; bj < 2; ++bj)
; #pragma unroll
;             for (int n = 0; n < 2; ++n) { ERES_LOAD(0, bj, n); asm volatile("" ::: "memory"); ERES_STORE(0, bj, n); asm volatile("" ::: "memory"); }
.LBB0_219:
	v_lshlrev_b64 v[150:151], 2, v[138:139]
	v_lshl_add_u64 v[146:147], v[144:145], 0, v[150:151]
	v_add_co_u32_e32 v148, vcc, 0x20000, v146
	s_mov_b32 s19, 0x120000
	s_nop 0
	v_addc_co_u32_e32 v149, vcc, 0, v147, vcc
	v_add_co_u32_e32 v152, vcc, 0x40000, v146
	global_load_dwordx4 v[178:181], v[146:147], off
	global_load_dwordx4 v[182:185], v[148:149], off
	v_addc_co_u32_e32 v153, vcc, 0, v147, vcc
	v_add_co_u32_e32 v154, vcc, 0x60000, v146
	v_readlane_b32 s26, v249, 61
	s_nop 0
	v_addc_co_u32_e32 v155, vcc, 0, v147, vcc
	v_add_co_u32_e32 v156, vcc, 0x100000, v146
	global_load_dwordx4 v[186:189], v[152:153], off
	global_load_dwordx4 v[190:193], v[154:155], off
	v_addc_co_u32_e32 v157, vcc, 0, v147, vcc
	v_add_co_u32_e32 v160, vcc, s19, v146
	v_readlane_b32 s27, v249, 62
	s_nop 0
	v_addc_co_u32_e32 v161, vcc, 0, v147, vcc
	v_add_co_u32_e32 v162, vcc, 0x140000, v146
	global_load_dwordx4 v[210:213], v[156:157], off
	global_load_dwordx4 v[214:217], v[160:161], off
	v_addc_co_u32_e32 v163, vcc, 0, v147, vcc
	v_add_co_u32_e32 v166, vcc, 0x160000, v146
	v_lshl_add_u64 v[142:143], s[26:27], 0, v[142:143]
	s_nop 0
	v_addc_co_u32_e32 v167, vcc, 0, v147, vcc
	global_load_dwordx4 v[218:221], v[162:163], off
	global_load_dwordx4 v[222:225], v[166:167], off
	global_load_dwordx4 v[240:243], v[136:137], off
	v_lshl_add_u64 v[142:143], v[142:143], 0, v[150:151]
	s_mov_b32 s21, 0x20000
	v_add_co_u32_e32 v144, vcc, s21, v142
	s_mov_b32 s21, 0x40000
	s_nop 0
	v_addc_co_u32_e32 v145, vcc, 0, v143, vcc
	v_add_co_u32_e32 v150, vcc, s21, v142
	s_mov_b32 s21, 0x60000
	s_nop 0
	v_addc_co_u32_e32 v151, vcc, 0, v143, vcc
	v_add_co_u32_e32 v158, vcc, s21, v142
	s_mov_b32 s21, 0x100000
	s_nop 0
	v_addc_co_u32_e32 v159, vcc, 0, v143, vcc
	v_add_co_u32_e32 v164, vcc, s21, v142
	s_nop 1
	v_addc_co_u32_e32 v165, vcc, 0, v143, vcc
	v_add_co_u32_e32 v168, vcc, s19, v142
	s_mov_b32 s19, 0x140000
	s_nop 0
	v_addc_co_u32_e32 v169, vcc, 0, v143, vcc
	v_add_co_u32_e32 v170, vcc, s19, v142
	s_mov_b32 s19, 0x160000
	s_nop 0
	v_addc_co_u32_e32 v171, vcc, 0, v143, vcc
	v_add_co_u32_e32 v172, vcc, s19, v142
	s_waitcnt vmcnt(0)
	v_pk_fma_f32 v[180:181], v[128:129], v[242:243], v[180:181]
	v_pk_fma_f32 v[178:179], v[126:127], v[240:241], v[178:179]
	v_pk_fma_f32 v[184:185], v[124:125], v[242:243], v[184:185]
	v_pk_fma_f32 v[182:183], v[122:123], v[240:241], v[182:183]
	v_pk_fma_f32 v[188:189], v[120:121], v[242:243], v[188:189]
	v_pk_fma_f32 v[186:187], v[118:119], v[240:241], v[186:187]
	v_pk_fma_f32 v[192:193], v[116:117], v[242:243], v[192:193]
	v_pk_fma_f32 v[190:191], v[114:115], v[240:241], v[190:191]
	v_pk_fma_f32 v[212:213], v[112:113], v[242:243], v[212:213]
	v_pk_fma_f32 v[210:211], v[110:111], v[240:241], v[210:211]
	v_pk_fma_f32 v[216:217], v[108:109], v[242:243], v[216:217]
	v_pk_fma_f32 v[214:215], v[106:107], v[240:241], v[214:215]
	v_pk_fma_f32 v[220:221], v[104:105], v[242:243], v[220:221]
	v_pk_fma_f32 v[218:219], v[102:103], v[240:241], v[218:219]
	global_load_dwordx4 v[126:129], v[146:147], off offset:64
	global_load_dwordx4 v[122:125], v[148:149], off offset:64
	global_load_dwordx4 v[118:121], v[152:153], off offset:64
	global_load_dwordx4 v[114:117], v[154:155], off offset:64
	global_load_dwordx4 v[110:113], v[156:157], off offset:64
	global_load_dwordx4 v[106:109], v[160:161], off offset:64
	global_load_dwordx4 v[102:105], v[162:163], off offset:64
	global_load_dwordx4 v[202:205], v[166:167], off offset:64
	global_load_dwordx4 v[244:247], v[136:137], off offset:64
	global_store_dwordx4 v[142:143], v[178:181], off
	global_store_dwordx4 v[144:145], v[182:185], off
	global_store_dwordx4 v[150:151], v[186:189], off
	global_store_dwordx4 v[158:159], v[190:193], off
	global_store_dwordx4 v[164:165], v[210:213], off
	global_store_dwordx4 v[168:169], v[214:217], off
	global_store_dwordx4 v[170:171], v[218:221], off
	v_pk_fma_f32 v[180:181], v[100:101], v[242:243], v[224:225]
	v_pk_fma_f32 v[178:179], v[98:99], v[240:241], v[222:223]
	v_addc_co_u32_e32 v173, vcc, 0, v143, vcc
	global_store_dwordx4 v[172:173], v[178:181], off
	s_waitcnt vmcnt(8)
; #define ERES_LOAD(q, bj, n) do { _Pragma("unroll") for (int ai = 0; ai < 2; ++ai) _Pragma("unroll") for (int m = 0; m < 4; ++m) \
;             tb[q][ai * 4 + m] = *(const GAS f32x4*)(bp + (size_t)(ai * HALF + m * 16) * DM + (bj) * HALF + (n) * 16); } while (0)
; #define ERES_STORE(q, bj, n) do { const f32x4 gv = *(const GAS f32x4*)(gp + (bj) * HALF + (n) * 16); \
;             _Pragma("unroll") for (int ai = 0; ai < 2; ++ai) _Pragma("unroll") for (int m = 0; m < 4; ++m) \
;                 *(GAS f32x4*)(op + (size_t)(ai * HALF + m * 16) * DM + (bj) * HALF + (n) * 16) = tb[q][ai * 4 + m] + gv * acc[ai][bj][m][n]; } while (0)
;     __device__ __forceinline__ void operator()(const f32x4 (&acc)[2][2][4][2], const Unit& u, int wr, int wc, int fr, int fq) const {
;     ...
; #pragma unroll
;         for (int bj = 0; bj < 2; ++bj)
; #pragma unroll
;             for (int n = 0; n < 2; ++n) { ERES_LOAD(0, bj, n); asm volatile("" ::: "memory"); ERES_STORE(0, bj, n); asm volatile("" ::: "memory"); }
	v_pk_fma_f32 v[128:129], v[96:97], v[246:247], v[128:129]
	v_pk_fma_f32 v[126:127], v[94:95], v[244:245], v[126:127]
	v_pk_fma_f32 v[124:125], v[92:93], v[246:247], v[124:125]
	v_pk_fma_f32 v[122:123], v[90:91], v[244:245], v[122:123]
	v_pk_fma_f32 v[120:121], v[88:89], v[246:247], v[120:121]
	v_pk_fma_f32 v[118:119], v[86:87], v[244:245], v[118:119]
	v_pk_fma_f32 v[116:117], v[84:85], v[246:247], v[116:117]
	v_pk_fma_f32 v[114:115], v[82:83], v[244:245], v[114:115]
	v_pk_fma_f32 v[112:113], v[80:81], v[246:247], v[112:113]
	v_pk_fma_f32 v[110:111], v[78:79], v[244:245], v[110:111]
	v_pk_fma_f32 v[108:109], v[76:77], v[246:247], v[108:109]
	v_pk_fma_f32 v[106:107], v[74:75], v[244:245], v[106:107]
	v_pk_fma_f32 v[104:105], v[72:73], v[246:247], v[104:105]
	v_pk_fma_f32 v[102:103], v[70:71], v[244:245], v[102:103]
	v_pk_fma_f32 v[204:205], v[68:69], v[246:247], v[204:205]
	v_pk_fma_f32 v[202:203], v[66:67], v[244:245], v[202:203]
	global_load_dwordx4 v[178:181], v[146:147], off offset:512
	global_load_dwordx4 v[182:185], v[148:149], off offset:512
	global_load_dwordx4 v[186:189], v[152:153], off offset:512
	global_load_dwordx4 v[190:193], v[154:155], off offset:512
	global_load_dwordx4 v[210:213], v[156:157], off offset:512
	global_load_dwordx4 v[214:217], v[160:161], off offset:512
	global_load_dwordx4 v[218:221], v[162:163], off offset:512
	global_load_dwordx4 v[222:225], v[166:167], off offset:512
	global_load_dwordx4 v[240:243], v[136:137], off offset:512
	global_store_dwordx4 v[142:143], v[126:129], off offset:64
	global_store_dwordx4 v[144:145], v[122:125], off offset:64
	global_store_dwordx4 v[150:151], v[118:121], off offset:64
	global_store_dwordx4 v[158:159], v[114:117], off offset:64
	global_store_dwordx4 v[164:165], v[110:113], off offset:64
	global_store_dwordx4 v[168:169], v[106:109], off offset:64
	global_store_dwordx4 v[170:171], v[102:105], off offset:64
	global_store_dwordx4 v[172:173], v[202:205], off offset:64
	s_waitcnt vmcnt(8)
	v_pk_fma_f32 v[180:181], v[64:65], v[242:243], v[180:181]
	v_pk_fma_f32 v[178:179], v[62:63], v[240:241], v[178:179]
	v_pk_fma_f32 v[184:185], v[60:61], v[242:243], v[184:185]
	v_pk_fma_f32 v[182:183], v[58:59], v[240:241], v[182:183]
	v_pk_fma_f32 v[188:189], v[56:57], v[242:243], v[188:189]
	v_pk_fma_f32 v[186:187], v[54:55], v[240:241], v[186:187]
	v_pk_fma_f32 v[192:193], v[52:53], v[242:243], v[192:193]
	v_pk_fma_f32 v[190:191], v[50:51], v[240:241], v[190:191]
	v_pk_fma_f32 v[212:213], v[48:49], v[242:243], v[212:213]
	v_pk_fma_f32 v[210:211], v[46:47], v[240:241], v[210:211]
	v_pk_fma_f32 v[216:217], v[40:41], v[242:243], v[216:217]
	v_pk_fma_f32 v[214:215], v[38:39], v[240:241], v[214:215]
	v_pk_fma_f32 v[220:221], v[32:33], v[242:243], v[220:221]
	v_pk_fma_f32 v[218:219], v[30:31], v[240:241], v[218:219]
	v_pk_fma_f32 v[224:225], v[24:25], v[242:243], v[224:225]
	v_pk_fma_f32 v[222:223], v[22:23], v[240:241], v[222:223]
	global_load_dwordx4 v[126:129], v[146:147], off offset:576
	s_nop 0
	global_load_dwordx4 v[122:125], v[148:149], off offset:576
	s_nop 0
	global_load_dwordx4 v[118:121], v[152:153], off offset:576
	s_nop 0
	global_load_dwordx4 v[114:117], v[154:155], off offset:576
	s_nop 0
	global_load_dwordx4 v[110:113], v[156:157], off offset:576
	global_load_dwordx4 v[106:109], v[160:161], off offset:576
	s_nop 0
	global_load_dwordx4 v[102:105], v[162:163], off offset:576
	s_nop 0
	global_load_dwordx4 v[202:205], v[166:167], off offset:576
	global_load_dwordx4 v[244:247], v[136:137], off offset:576
	global_store_dwordx4 v[142:143], v[178:181], off offset:512
	global_store_dwordx4 v[144:145], v[182:185], off offset:512
	global_store_dwordx4 v[150:151], v[186:189], off offset:512
	global_store_dwordx4 v[158:159], v[190:193], off offset:512
	global_store_dwordx4 v[164:165], v[210:213], off offset:512
	global_store_dwordx4 v[168:169], v[214:217], off offset:512
	global_store_dwordx4 v[170:171], v[218:221], off offset:512
	global_store_dwordx4 v[172:173], v[222:225], off offset:512
	s_waitcnt vmcnt(8)
	v_pk_fma_f32 v[128:129], v[44:45], v[246:247], v[128:129]
	v_pk_fma_f32 v[126:127], v[42:43], v[244:245], v[126:127]
	v_pk_fma_f32 v[124:125], v[36:37], v[246:247], v[124:125]
	v_pk_fma_f32 v[122:123], v[34:35], v[244:245], v[122:123]
	v_pk_fma_f32 v[120:121], v[28:29], v[246:247], v[120:121]
	v_pk_fma_f32 v[118:119], v[26:27], v[244:245], v[118:119]
	v_pk_fma_f32 v[116:117], v[20:21], v[246:247], v[116:117]
	v_pk_fma_f32 v[114:115], v[18:19], v[244:245], v[114:115]
	v_pk_fma_f32 v[112:113], v[16:17], v[246:247], v[112:113]
	v_pk_fma_f32 v[110:111], v[14:15], v[244:245], v[110:111]
	v_pk_fma_f32 v[108:109], v[12:13], v[246:247], v[108:109]
	v_pk_fma_f32 v[106:107], v[10:11], v[244:245], v[106:107]
	v_pk_fma_f32 v[104:105], v[8:9], v[246:247], v[104:105]
	v_pk_fma_f32 v[102:103], v[6:7], v[244:245], v[102:103]
	v_pk_fma_f32 v[204:205], v[4:5], v[246:247], v[204:205]
	v_pk_fma_f32 v[202:203], v[2:3], v[244:245], v[202:203]
	global_store_dwordx4 v[142:143], v[126:129], off offset:576
	global_store_dwordx4 v[144:145], v[122:125], off offset:576
	global_store_dwordx4 v[150:151], v[118:121], off offset:576
	global_store_dwordx4 v[158:159], v[114:117], off offset:576
	global_store_dwordx4 v[164:165], v[110:113], off offset:576
	global_store_dwordx4 v[168:169], v[106:109], off offset:576
	global_store_dwordx4 v[170:171], v[102:105], off offset:576
	global_store_dwordx4 v[172:173], v[202:205], off offset:576
